# v9: GEMM1 gate-tile epilogue reuses sigmoid(g_b) computed for the ratio (saved in spare VGPRs) instead of recomputing
# speedup vs baseline: 1.0067x; 1.0067x over previous
; __device__ __forceinline__ f32x4 sigm4(f32x4 v) { return (f32x4){sigmoid_f(v[0]), sigmoid_f(v[1]), sigmoid_f(v[2]), sigmoid_f(v[3])}; }
;     __device__ __forceinline__ void operator()(const f32x4 (&acc)[2][2][4][2], const pg8::Unit& u, int wr, int wc, int fr, int fq) const {
;     ...
;                         f32x4 v0 = acc[ai][bj][m][0], v1 = acc[ai][bj][m][1];
;                         if (act == 5) { v0 = sigm4(v0); v1 = sigm4(v1);
;                             if (bj == 0) { const f32x4 b0 = sigm4(acc[ai][1][m][0]), b1 = sigm4(acc[ai][1][m][1]);
; #pragma unroll
;                                 for (int e = 0; e < 4; ++e) { v0[e] *= __builtin_amdgcn_rcpf(fmaxf(b0[e], 1e-20f)); v1[e] *= __builtin_amdgcn_rcpf(fmaxf(b1[e], 1e-20f)); } } }
.LBB0_198:
	s_andn2_b64 vcc, exec, s[16:17]
	s_cbranch_vccnz .LBB0_200
	v_mul_f32_e32 v147, 0xbfb8aa3b, v116
	v_exp_f32_e32 v147, v147
	v_mul_f32_e32 v148, 0xbfb8aa3b, v117
	v_exp_f32_e32 v148, v148
	v_mul_f32_e32 v152, 0xbfb8aa3b, v119
	v_add_f32_e32 v147, 1.0, v147
	v_exp_f32_e32 v153, v152
	v_add_f32_e32 v149, 1.0, v148
	v_rcp_f32_e32 v148, v147
	v_mul_f32_e32 v147, 0xbfb8aa3b, v118
	v_exp_f32_e32 v147, v147
	v_mul_f32_e32 v160, 0xbfb8aa3b, v123
	v_exp_f32_e32 v160, v160
	v_mul_f32_e32 v168, 0xbfb8aa3b, v115
	v_add_f32_e32 v147, 1.0, v147
	v_rcp_f32_e32 v152, v147
	v_add_f32_e32 v147, 1.0, v153
	v_mul_f32_e32 v153, 0xbfb8aa3b, v124
	v_exp_f32_e32 v154, v153
	v_mul_f32_e32 v153, 0xbfb8aa3b, v125
	v_exp_f32_e32 v155, v153
	v_rcp_f32_e32 v153, v147
	v_add_f32_e32 v147, 1.0, v154
	v_rcp_f32_e32 v154, v147
	v_add_f32_e32 v147, 1.0, v155
	v_mul_f32_e32 v155, 0xbfb8aa3b, v126
	v_exp_f32_e32 v156, v155
	v_mul_f32_e32 v155, 0xbfb8aa3b, v127
	v_exp_f32_e32 v157, v155
	v_rcp_f32_e32 v155, v147
	v_add_f32_e32 v147, 1.0, v156
	v_rcp_f32_e32 v156, v147
	v_add_f32_e32 v147, 1.0, v157
	v_mul_f32_e32 v157, 0xbfb8aa3b, v120
	v_exp_f32_e32 v158, v157
	v_mul_f32_e32 v157, 0xbfb8aa3b, v121
	v_exp_f32_e32 v159, v157
	v_rcp_f32_e32 v157, v147
	v_add_f32_e32 v147, 1.0, v158
	v_rcp_f32_e32 v240, v147
	v_add_f32_e32 v158, 1.0, v159
	v_mul_f32_e32 v159, 0xbfb8aa3b, v122
	v_exp_f32_e32 v159, v159
	v_rcp_f32_e32 v241, v158
	v_exp_f32_e32 v168, v168
	v_max_f32_e32 v147, 0x1e3ce508, v240
	v_add_f32_e32 v158, 1.0, v159
	v_mul_f32_e32 v159, 0xbfb8aa3b, v112
	v_rcp_f32_e32 v242, v158
	v_add_f32_e32 v158, 1.0, v160
	v_exp_f32_e32 v159, v159
	v_mul_f32_e32 v160, 0xbfb8aa3b, v113
	v_exp_f32_e32 v160, v160
	v_rcp_f32_e32 v243, v158
	v_add_f32_e32 v158, 1.0, v159
	v_rcp_f32_e32 v244, v158
	v_add_f32_e32 v158, 1.0, v160
	v_mul_f32_e32 v160, 0xbfb8aa3b, v114
	v_exp_f32_e32 v160, v160
	v_rcp_f32_e32 v245, v158
	v_rcp_f32_e32 v149, v149
	v_add_f32_e32 v158, 1.0, v160
	v_rcp_f32_e32 v246, v158
	v_add_f32_e32 v158, 1.0, v168
	v_rcp_f32_e32 v247, v158
	v_rcp_f32_e32 v158, v147
	v_max_f32_e32 v147, 0x1e3ce508, v244
	v_rcp_f32_e32 v160, v147
	v_max_f32_e32 v147, 0x1e3ce508, v241
	v_rcp_f32_e32 v159, v147
	v_max_f32_e32 v147, 0x1e3ce508, v245
	v_rcp_f32_e32 v161, v147
	v_max_f32_e32 v147, 0x1e3ce508, v242
	v_rcp_f32_e32 v168, v147
	v_max_f32_e32 v147, 0x1e3ce508, v246
	v_rcp_f32_e32 v170, v147
	v_max_f32_e32 v147, 0x1e3ce508, v243
	v_rcp_f32_e32 v169, v147
	v_max_f32_e32 v147, 0x1e3ce508, v247
	v_rcp_f32_e32 v171, v147
	v_pk_mul_f32 v[154:155], v[154:155], v[158:159]
	v_pk_mul_f32 v[156:157], v[156:157], v[168:169]
	v_pk_mul_f32 v[158:159], v[148:149], v[160:161]
	v_pk_mul_f32 v[160:161], v[152:153], v[170:171]

; __device__ __forceinline__ f32x4 sigm4(f32x4 v) { return (f32x4){sigmoid_f(v[0]), sigmoid_f(v[1]), sigmoid_f(v[2]), sigmoid_f(v[3])}; }
;     __device__ __forceinline__ void operator()(const f32x4 (&acc)[2][2][4][2], const pg8::Unit& u, int wr, int wc, int fr, int fq) const {
;     ...
;                     for (int bj = 0; bj < 2; ++bj) {
;                         f32x4 v0 = acc[ai][bj][m][0], v1 = acc[ai][bj][m][1];
;                         if (act == 5) { v0 = sigm4(v0); v1 = sigm4(v1);
.LBB0_212:
	s_andn2_b64 vcc, exec, s[16:17]
	s_cbranch_vccnz .LBB0_214
	v_mov_b64_e32 v[154:155], v[240:241]
	v_mov_b64_e32 v[156:157], v[242:243]
	v_mov_b64_e32 v[158:159], v[244:245]
	v_mov_b64_e32 v[160:161], v[246:247]

; __device__ __forceinline__ f32x4 sigm4(f32x4 v) { return (f32x4){sigmoid_f(v[0]), sigmoid_f(v[1]), sigmoid_f(v[2]), sigmoid_f(v[3])}; }
;     __device__ __forceinline__ void operator()(const f32x4 (&acc)[2][2][4][2], const pg8::Unit& u, int wr, int wc, int fr, int fq) const {
;     ...
;                         f32x4 v0 = acc[ai][bj][m][0], v1 = acc[ai][bj][m][1];
;                         if (act == 5) { v0 = sigm4(v0); v1 = sigm4(v1);
;                             if (bj == 0) { const f32x4 b0 = sigm4(acc[ai][1][m][0]), b1 = sigm4(acc[ai][1][m][1]);
; #pragma unroll
;                                 for (int e = 0; e < 4; ++e) { v0[e] *= __builtin_amdgcn_rcpf(fmaxf(b0[e], 1e-20f)); v1[e] *= __builtin_amdgcn_rcpf(fmaxf(b1[e], 1e-20f)); } } }
.LBB0_226:
	s_andn2_b64 vcc, exec, s[16:17]
	s_cbranch_vccnz .LBB0_228
	v_mul_f32_e32 v147, 0xbfb8aa3b, v100
	v_exp_f32_e32 v147, v147
	v_mul_f32_e32 v152, 0xbfb8aa3b, v101
	v_exp_f32_e32 v152, v152
	v_mul_f32_e32 v154, 0xbfb8aa3b, v103
	v_add_f32_e32 v147, 1.0, v147
	v_exp_f32_e32 v154, v154
	v_add_f32_e32 v153, 1.0, v152
	v_rcp_f32_e32 v152, v147
	v_mul_f32_e32 v147, 0xbfb8aa3b, v102
	v_exp_f32_e32 v147, v147
	v_mul_f32_e32 v155, 0xbfb8aa3b, v109
	v_exp_f32_e32 v155, v155
	v_mul_f32_e32 v167, 0xbfb8aa3b, v107
	v_add_f32_e32 v147, 1.0, v147
	v_rcp_f32_e32 v160, v147
	v_add_f32_e32 v147, 1.0, v154
	v_mul_f32_e32 v154, 0xbfb8aa3b, v108
	v_exp_f32_e32 v154, v154
	v_rcp_f32_e32 v161, v147
	v_exp_f32_e32 v167, v167
	v_mul_f32_e32 v168, 0xbfb8aa3b, v99
	v_add_f32_e32 v147, 1.0, v154
	v_rcp_f32_e32 v154, v147
	v_add_f32_e32 v147, 1.0, v155
	v_mul_f32_e32 v155, 0xbfb8aa3b, v110
	v_exp_f32_e32 v156, v155
	v_mul_f32_e32 v155, 0xbfb8aa3b, v111
	v_exp_f32_e32 v157, v155
	v_rcp_f32_e32 v155, v147
	v_add_f32_e32 v147, 1.0, v156
	v_rcp_f32_e32 v156, v147
	v_add_f32_e32 v147, 1.0, v157
	v_mul_f32_e32 v157, 0xbfb8aa3b, v104
	v_exp_f32_e32 v158, v157
	v_mul_f32_e32 v157, 0xbfb8aa3b, v105
	v_exp_f32_e32 v159, v157
	v_rcp_f32_e32 v157, v147
	v_add_f32_e32 v147, 1.0, v158
	v_rcp_f32_e32 v240, v147
	v_add_f32_e32 v158, 1.0, v159
	v_mul_f32_e32 v159, 0xbfb8aa3b, v106
	v_exp_f32_e32 v159, v159
	v_rcp_f32_e32 v241, v158
	v_exp_f32_e32 v168, v168
	v_max_f32_e32 v147, 0x1e3ce508, v240
	v_add_f32_e32 v158, 1.0, v159
	v_mul_f32_e32 v159, 0xbfb8aa3b, v96
	v_rcp_f32_e32 v242, v158
	v_add_f32_e32 v158, 1.0, v167
	v_exp_f32_e32 v159, v159
	v_mul_f32_e32 v167, 0xbfb8aa3b, v97
	v_exp_f32_e32 v167, v167
	v_rcp_f32_e32 v243, v158
	v_add_f32_e32 v158, 1.0, v159
	v_rcp_f32_e32 v244, v158
	v_add_f32_e32 v158, 1.0, v167
	v_mul_f32_e32 v167, 0xbfb8aa3b, v98
	v_exp_f32_e32 v167, v167
	v_rcp_f32_e32 v245, v158
	v_rcp_f32_e32 v153, v153
	v_add_f32_e32 v158, 1.0, v167
	v_rcp_f32_e32 v246, v158
	v_add_f32_e32 v158, 1.0, v168
	v_rcp_f32_e32 v247, v158
	v_rcp_f32_e32 v158, v147
	v_max_f32_e32 v147, 0x1e3ce508, v244
	v_rcp_f32_e32 v168, v147
	v_max_f32_e32 v147, 0x1e3ce508, v241
	v_rcp_f32_e32 v159, v147
	v_max_f32_e32 v147, 0x1e3ce508, v245
	v_rcp_f32_e32 v169, v147
	v_max_f32_e32 v147, 0x1e3ce508, v242
	v_rcp_f32_e32 v170, v147
	v_max_f32_e32 v147, 0x1e3ce508, v246
	v_rcp_f32_e32 v172, v147
	v_max_f32_e32 v147, 0x1e3ce508, v243
	v_rcp_f32_e32 v171, v147
	v_max_f32_e32 v147, 0x1e3ce508, v247
	v_rcp_f32_e32 v173, v147
	v_pk_mul_f32 v[154:155], v[154:155], v[158:159]
	v_pk_mul_f32 v[156:157], v[156:157], v[170:171]
	v_pk_mul_f32 v[158:159], v[152:153], v[168:169]
	v_pk_mul_f32 v[160:161], v[160:161], v[172:173]

; __device__ __forceinline__ f32x4 sigm4(f32x4 v) { return (f32x4){sigmoid_f(v[0]), sigmoid_f(v[1]), sigmoid_f(v[2]), sigmoid_f(v[3])}; }
;     __device__ __forceinline__ void operator()(const f32x4 (&acc)[2][2][4][2], const pg8::Unit& u, int wr, int wc, int fr, int fq) const {
;     ...
;                         f32x4 v0 = acc[ai][bj][m][0], v1 = acc[ai][bj][m][1];
;                         if (act == 5) { v0 = sigm4(v0); v1 = sigm4(v1);
;                             if (bj == 0) { const f32x4 b0 = sigm4(acc[ai][1][m][0]), b1 = sigm4(acc[ai][1][m][1]);
; #pragma unroll
;                                 for (int e = 0; e < 4; ++e) { v0[e] *= __builtin_amdgcn_rcpf(fmaxf(b0[e], 1e-20f)); v1[e] *= __builtin_amdgcn_rcpf(fmaxf(b1[e], 1e-20f)); } } }
.LBB0_254:
	s_andn2_b64 vcc, exec, s[16:17]
	s_cbranch_vccnz .LBB0_256
	v_mul_f32_e32 v147, 0xbfb8aa3b, v84
	v_exp_f32_e32 v147, v147
	v_mul_f32_e32 v152, 0xbfb8aa3b, v85
	v_exp_f32_e32 v152, v152
	v_mul_f32_e32 v154, 0xbfb8aa3b, v87
	v_add_f32_e32 v147, 1.0, v147
	v_exp_f32_e32 v154, v154
	v_add_f32_e32 v153, 1.0, v152
	v_rcp_f32_e32 v152, v147
	v_mul_f32_e32 v147, 0xbfb8aa3b, v86
	v_exp_f32_e32 v147, v147
	v_mul_f32_e32 v155, 0xbfb8aa3b, v93
	v_exp_f32_e32 v155, v155
	v_mul_f32_e32 v167, 0xbfb8aa3b, v91
	v_add_f32_e32 v147, 1.0, v147
	v_rcp_f32_e32 v160, v147
	v_add_f32_e32 v147, 1.0, v154
	v_mul_f32_e32 v154, 0xbfb8aa3b, v92
	v_exp_f32_e32 v154, v154
	v_rcp_f32_e32 v161, v147
	v_exp_f32_e32 v167, v167
	v_mul_f32_e32 v168, 0xbfb8aa3b, v83
	v_add_f32_e32 v147, 1.0, v154
	v_rcp_f32_e32 v154, v147
	v_add_f32_e32 v147, 1.0, v155
	v_mul_f32_e32 v155, 0xbfb8aa3b, v94
	v_exp_f32_e32 v156, v155
	v_mul_f32_e32 v155, 0xbfb8aa3b, v95
	v_exp_f32_e32 v157, v155
	v_rcp_f32_e32 v155, v147
	v_add_f32_e32 v147, 1.0, v156
	v_rcp_f32_e32 v156, v147
	v_add_f32_e32 v147, 1.0, v157
	v_mul_f32_e32 v157, 0xbfb8aa3b, v88
	v_exp_f32_e32 v158, v157
	v_mul_f32_e32 v157, 0xbfb8aa3b, v89
	v_exp_f32_e32 v159, v157
	v_rcp_f32_e32 v157, v147
	v_add_f32_e32 v147, 1.0, v158
	v_rcp_f32_e32 v240, v147
	v_add_f32_e32 v158, 1.0, v159
	v_mul_f32_e32 v159, 0xbfb8aa3b, v90
	v_exp_f32_e32 v159, v159
	v_rcp_f32_e32 v241, v158
	v_exp_f32_e32 v168, v168
	v_max_f32_e32 v147, 0x1e3ce508, v240
	v_add_f32_e32 v158, 1.0, v159
	v_mul_f32_e32 v159, 0xbfb8aa3b, v80
	v_rcp_f32_e32 v242, v158
	v_add_f32_e32 v158, 1.0, v167
	v_exp_f32_e32 v159, v159
	v_mul_f32_e32 v167, 0xbfb8aa3b, v81
	v_exp_f32_e32 v167, v167
	v_rcp_f32_e32 v243, v158
	v_add_f32_e32 v158, 1.0, v159
	v_rcp_f32_e32 v244, v158
	v_add_f32_e32 v158, 1.0, v167
	v_mul_f32_e32 v167, 0xbfb8aa3b, v82
	v_exp_f32_e32 v167, v167
	v_rcp_f32_e32 v245, v158
	v_rcp_f32_e32 v153, v153
	v_add_f32_e32 v158, 1.0, v167
	v_rcp_f32_e32 v246, v158
	v_add_f32_e32 v158, 1.0, v168
	v_rcp_f32_e32 v247, v158
	v_rcp_f32_e32 v158, v147
	v_max_f32_e32 v147, 0x1e3ce508, v244
	v_rcp_f32_e32 v168, v147
	v_max_f32_e32 v147, 0x1e3ce508, v241
	v_rcp_f32_e32 v159, v147
	v_max_f32_e32 v147, 0x1e3ce508, v245
	v_rcp_f32_e32 v169, v147
	v_max_f32_e32 v147, 0x1e3ce508, v242
	v_rcp_f32_e32 v170, v147
	v_max_f32_e32 v147, 0x1e3ce508, v246
	v_rcp_f32_e32 v172, v147
	v_max_f32_e32 v147, 0x1e3ce508, v243
	v_rcp_f32_e32 v171, v147
	v_max_f32_e32 v147, 0x1e3ce508, v247
	v_rcp_f32_e32 v173, v147
	v_pk_mul_f32 v[154:155], v[154:155], v[158:159]
	v_pk_mul_f32 v[156:157], v[156:157], v[170:171]
	v_pk_mul_f32 v[158:159], v[152:153], v[168:169]
	v_pk_mul_f32 v[160:161], v[160:161], v[172:173]

; __device__ __forceinline__ f32x4 sigm4(f32x4 v) { return (f32x4){sigmoid_f(v[0]), sigmoid_f(v[1]), sigmoid_f(v[2]), sigmoid_f(v[3])}; }
;     __device__ __forceinline__ void operator()(const f32x4 (&acc)[2][2][4][2], const pg8::Unit& u, int wr, int wc, int fr, int fq) const {
;     ...
;                         f32x4 v0 = acc[ai][bj][m][0], v1 = acc[ai][bj][m][1];
;                         if (act == 5) { v0 = sigm4(v0); v1 = sigm4(v1);
;                             if (bj == 0) { const f32x4 b0 = sigm4(acc[ai][1][m][0]), b1 = sigm4(acc[ai][1][m][1]);
; #pragma unroll
;                                 for (int e = 0; e < 4; ++e) { v0[e] *= __builtin_amdgcn_rcpf(fmaxf(b0[e], 1e-20f)); v1[e] *= __builtin_amdgcn_rcpf(fmaxf(b1[e], 1e-20f)); } } }
.LBB0_282:
	s_andn2_b64 vcc, exec, s[16:17]
	s_cbranch_vccnz .LBB0_284
	v_mul_f32_e32 v147, 0xbfb8aa3b, v68
	v_exp_f32_e32 v147, v147
	v_mul_f32_e32 v152, 0xbfb8aa3b, v69
	v_exp_f32_e32 v152, v152
	v_mul_f32_e32 v154, 0xbfb8aa3b, v71
	v_add_f32_e32 v147, 1.0, v147
	v_exp_f32_e32 v154, v154
	v_add_f32_e32 v153, 1.0, v152
	v_rcp_f32_e32 v152, v147
	v_mul_f32_e32 v147, 0xbfb8aa3b, v70
	v_exp_f32_e32 v147, v147
	v_mul_f32_e32 v155, 0xbfb8aa3b, v77
	v_exp_f32_e32 v155, v155
	v_mul_f32_e32 v167, 0xbfb8aa3b, v75
	v_add_f32_e32 v147, 1.0, v147
	v_rcp_f32_e32 v160, v147
	v_add_f32_e32 v147, 1.0, v154
	v_mul_f32_e32 v154, 0xbfb8aa3b, v76
	v_exp_f32_e32 v154, v154
	v_rcp_f32_e32 v161, v147
	v_exp_f32_e32 v167, v167
	v_mul_f32_e32 v168, 0xbfb8aa3b, v67
	v_add_f32_e32 v147, 1.0, v154
	v_rcp_f32_e32 v154, v147
	v_add_f32_e32 v147, 1.0, v155
	v_mul_f32_e32 v155, 0xbfb8aa3b, v78
	v_exp_f32_e32 v156, v155
	v_mul_f32_e32 v155, 0xbfb8aa3b, v79
	v_exp_f32_e32 v157, v155
	v_rcp_f32_e32 v155, v147
	v_add_f32_e32 v147, 1.0, v156
	v_rcp_f32_e32 v156, v147
	v_add_f32_e32 v147, 1.0, v157
	v_mul_f32_e32 v157, 0xbfb8aa3b, v72
	v_exp_f32_e32 v158, v157
	v_mul_f32_e32 v157, 0xbfb8aa3b, v73
	v_exp_f32_e32 v159, v157
	v_rcp_f32_e32 v157, v147
	v_add_f32_e32 v147, 1.0, v158
	v_rcp_f32_e32 v240, v147
	v_add_f32_e32 v158, 1.0, v159
	v_mul_f32_e32 v159, 0xbfb8aa3b, v74
	v_exp_f32_e32 v159, v159
	v_rcp_f32_e32 v241, v158
	v_exp_f32_e32 v168, v168
	v_max_f32_e32 v147, 0x1e3ce508, v240
	v_add_f32_e32 v158, 1.0, v159
	v_mul_f32_e32 v159, 0xbfb8aa3b, v64
	v_rcp_f32_e32 v242, v158
	v_add_f32_e32 v158, 1.0, v167
	v_exp_f32_e32 v159, v159
	v_mul_f32_e32 v167, 0xbfb8aa3b, v65
	v_exp_f32_e32 v167, v167
	v_rcp_f32_e32 v243, v158
	v_add_f32_e32 v158, 1.0, v159
	v_rcp_f32_e32 v244, v158
	v_add_f32_e32 v158, 1.0, v167
	v_mul_f32_e32 v167, 0xbfb8aa3b, v66
	v_exp_f32_e32 v167, v167
	v_rcp_f32_e32 v245, v158
	v_rcp_f32_e32 v153, v153
	v_add_f32_e32 v158, 1.0, v167
	v_rcp_f32_e32 v246, v158
	v_add_f32_e32 v158, 1.0, v168
	v_rcp_f32_e32 v247, v158
	v_rcp_f32_e32 v158, v147
	v_max_f32_e32 v147, 0x1e3ce508, v244
	v_rcp_f32_e32 v168, v147
	v_max_f32_e32 v147, 0x1e3ce508, v241
	v_rcp_f32_e32 v159, v147
	v_max_f32_e32 v147, 0x1e3ce508, v245
	v_rcp_f32_e32 v169, v147
	v_max_f32_e32 v147, 0x1e3ce508, v242
	v_rcp_f32_e32 v170, v147
	v_max_f32_e32 v147, 0x1e3ce508, v246
	v_rcp_f32_e32 v172, v147
	v_max_f32_e32 v147, 0x1e3ce508, v243
	v_rcp_f32_e32 v171, v147
	v_max_f32_e32 v147, 0x1e3ce508, v247
	v_rcp_f32_e32 v173, v147
	v_pk_mul_f32 v[154:155], v[154:155], v[158:159]
	v_pk_mul_f32 v[156:157], v[156:157], v[170:171]
	v_pk_mul_f32 v[158:159], v[152:153], v[168:169]
	v_pk_mul_f32 v[160:161], v[160:161], v[172:173]

; __device__ __forceinline__ f32x4 sigm4(f32x4 v) { return (f32x4){sigmoid_f(v[0]), sigmoid_f(v[1]), sigmoid_f(v[2]), sigmoid_f(v[3])}; }
;     __device__ __forceinline__ void operator()(const f32x4 (&acc)[2][2][4][2], const pg8::Unit& u, int wr, int wc, int fr, int fq) const {
;     ...
;                         f32x4 v0 = acc[ai][bj][m][0], v1 = acc[ai][bj][m][1];
;                         if (act == 5) { v0 = sigm4(v0); v1 = sigm4(v1);
;                             if (bj == 0) { const f32x4 b0 = sigm4(acc[ai][1][m][0]), b1 = sigm4(acc[ai][1][m][1]);
; #pragma unroll
;                                 for (int e = 0; e < 4; ++e) { v0[e] *= __builtin_amdgcn_rcpf(fmaxf(b0[e], 1e-20f)); v1[e] *= __builtin_amdgcn_rcpf(fmaxf(b1[e], 1e-20f)); } } }
.LBB0_310:
	s_andn2_b64 vcc, exec, s[16:17]
	s_cbranch_vccnz .LBB0_312
	v_mul_f32_e32 v147, 0xbfb8aa3b, v52
	v_exp_f32_e32 v147, v147
	v_mul_f32_e32 v152, 0xbfb8aa3b, v53
	v_exp_f32_e32 v152, v152
	v_mul_f32_e32 v154, 0xbfb8aa3b, v55
	v_add_f32_e32 v147, 1.0, v147
	v_exp_f32_e32 v154, v154
	v_add_f32_e32 v153, 1.0, v152
	v_rcp_f32_e32 v152, v147
	v_mul_f32_e32 v147, 0xbfb8aa3b, v54
	v_exp_f32_e32 v147, v147
	v_mul_f32_e32 v155, 0xbfb8aa3b, v61
	v_exp_f32_e32 v155, v155
	v_mul_f32_e32 v167, 0xbfb8aa3b, v59
	v_add_f32_e32 v147, 1.0, v147
	v_rcp_f32_e32 v160, v147
	v_add_f32_e32 v147, 1.0, v154
	v_mul_f32_e32 v154, 0xbfb8aa3b, v60
	v_exp_f32_e32 v154, v154
	v_rcp_f32_e32 v161, v147
	v_exp_f32_e32 v167, v167
	v_mul_f32_e32 v168, 0xbfb8aa3b, v51
	v_add_f32_e32 v147, 1.0, v154
	v_rcp_f32_e32 v154, v147
	v_add_f32_e32 v147, 1.0, v155
	v_mul_f32_e32 v155, 0xbfb8aa3b, v62
	v_exp_f32_e32 v156, v155
	v_mul_f32_e32 v155, 0xbfb8aa3b, v63
	v_exp_f32_e32 v157, v155
	v_rcp_f32_e32 v155, v147
	v_add_f32_e32 v147, 1.0, v156
	v_rcp_f32_e32 v156, v147
	v_add_f32_e32 v147, 1.0, v157
	v_mul_f32_e32 v157, 0xbfb8aa3b, v56
	v_exp_f32_e32 v158, v157
	v_mul_f32_e32 v157, 0xbfb8aa3b, v57
	v_exp_f32_e32 v159, v157
	v_rcp_f32_e32 v157, v147
	v_add_f32_e32 v147, 1.0, v158
	v_rcp_f32_e32 v240, v147
	v_add_f32_e32 v158, 1.0, v159
	v_mul_f32_e32 v159, 0xbfb8aa3b, v58
	v_exp_f32_e32 v159, v159
	v_rcp_f32_e32 v241, v158
	v_exp_f32_e32 v168, v168
	v_max_f32_e32 v147, 0x1e3ce508, v240
	v_add_f32_e32 v158, 1.0, v159
	v_mul_f32_e32 v159, 0xbfb8aa3b, v48
	v_rcp_f32_e32 v242, v158
	v_add_f32_e32 v158, 1.0, v167
	v_exp_f32_e32 v159, v159
	v_mul_f32_e32 v167, 0xbfb8aa3b, v49
	v_exp_f32_e32 v167, v167
	v_rcp_f32_e32 v243, v158
	v_add_f32_e32 v158, 1.0, v159
	v_rcp_f32_e32 v244, v158
	v_add_f32_e32 v158, 1.0, v167
	v_mul_f32_e32 v167, 0xbfb8aa3b, v50
	v_exp_f32_e32 v167, v167
	v_rcp_f32_e32 v245, v158
	v_rcp_f32_e32 v153, v153
	v_add_f32_e32 v158, 1.0, v167
	v_rcp_f32_e32 v246, v158
	v_add_f32_e32 v158, 1.0, v168
	v_rcp_f32_e32 v247, v158
	v_rcp_f32_e32 v158, v147
	v_max_f32_e32 v147, 0x1e3ce508, v244
	v_rcp_f32_e32 v168, v147
	v_max_f32_e32 v147, 0x1e3ce508, v241
	v_rcp_f32_e32 v159, v147
	v_max_f32_e32 v147, 0x1e3ce508, v245
	v_rcp_f32_e32 v169, v147
	v_max_f32_e32 v147, 0x1e3ce508, v242
	v_rcp_f32_e32 v170, v147
	v_max_f32_e32 v147, 0x1e3ce508, v246
	v_rcp_f32_e32 v172, v147
	v_max_f32_e32 v147, 0x1e3ce508, v243
	v_rcp_f32_e32 v171, v147
	v_max_f32_e32 v147, 0x1e3ce508, v247
	v_rcp_f32_e32 v173, v147
	v_pk_mul_f32 v[154:155], v[154:155], v[158:159]
	v_pk_mul_f32 v[156:157], v[156:157], v[170:171]
	v_pk_mul_f32 v[158:159], v[152:153], v[168:169]
	v_pk_mul_f32 v[160:161], v[160:161], v[172:173]

; __device__ __forceinline__ f32x4 sigm4(f32x4 v) { return (f32x4){sigmoid_f(v[0]), sigmoid_f(v[1]), sigmoid_f(v[2]), sigmoid_f(v[3])}; }
;     __device__ __forceinline__ void operator()(const f32x4 (&acc)[2][2][4][2], const pg8::Unit& u, int wr, int wc, int fr, int fq) const {
;     ...
;                         f32x4 v0 = acc[ai][bj][m][0], v1 = acc[ai][bj][m][1];
;                         if (act == 5) { v0 = sigm4(v0); v1 = sigm4(v1);
;                             if (bj == 0) { const f32x4 b0 = sigm4(acc[ai][1][m][0]), b1 = sigm4(acc[ai][1][m][1]);
; #pragma unroll
;                                 for (int e = 0; e < 4; ++e) { v0[e] *= __builtin_amdgcn_rcpf(fmaxf(b0[e], 1e-20f)); v1[e] *= __builtin_amdgcn_rcpf(fmaxf(b1[e], 1e-20f)); } } }
.LBB0_338:
	s_andn2_b64 vcc, exec, s[16:17]
	s_cbranch_vccnz .LBB0_340
	v_mul_f32_e32 v147, 0xbfb8aa3b, v36
	v_exp_f32_e32 v147, v147
	v_mul_f32_e32 v152, 0xbfb8aa3b, v37
	v_exp_f32_e32 v152, v152
	v_mul_f32_e32 v154, 0xbfb8aa3b, v39
	v_add_f32_e32 v147, 1.0, v147
	v_exp_f32_e32 v154, v154
	v_add_f32_e32 v153, 1.0, v152
	v_rcp_f32_e32 v152, v147
	v_mul_f32_e32 v147, 0xbfb8aa3b, v38
	v_exp_f32_e32 v147, v147
	v_mul_f32_e32 v155, 0xbfb8aa3b, v45
	v_exp_f32_e32 v155, v155
	v_mul_f32_e32 v167, 0xbfb8aa3b, v43
	v_add_f32_e32 v147, 1.0, v147
	v_rcp_f32_e32 v160, v147
	v_add_f32_e32 v147, 1.0, v154
	v_mul_f32_e32 v154, 0xbfb8aa3b, v44
	v_exp_f32_e32 v154, v154
	v_rcp_f32_e32 v161, v147
	v_exp_f32_e32 v167, v167
	v_mul_f32_e32 v168, 0xbfb8aa3b, v35
	v_add_f32_e32 v147, 1.0, v154
	v_rcp_f32_e32 v154, v147
	v_add_f32_e32 v147, 1.0, v155
	v_mul_f32_e32 v155, 0xbfb8aa3b, v46
	v_exp_f32_e32 v156, v155
	v_mul_f32_e32 v155, 0xbfb8aa3b, v47
	v_exp_f32_e32 v157, v155
	v_rcp_f32_e32 v155, v147
	v_add_f32_e32 v147, 1.0, v156
	v_rcp_f32_e32 v156, v147
	v_add_f32_e32 v147, 1.0, v157
	v_mul_f32_e32 v157, 0xbfb8aa3b, v40
	v_exp_f32_e32 v158, v157
	v_mul_f32_e32 v157, 0xbfb8aa3b, v41
	v_exp_f32_e32 v159, v157
	v_rcp_f32_e32 v157, v147
	v_add_f32_e32 v147, 1.0, v158
	v_rcp_f32_e32 v240, v147
	v_add_f32_e32 v158, 1.0, v159
	v_mul_f32_e32 v159, 0xbfb8aa3b, v42
	v_exp_f32_e32 v159, v159
	v_rcp_f32_e32 v241, v158
	v_exp_f32_e32 v168, v168
	v_max_f32_e32 v147, 0x1e3ce508, v240
	v_add_f32_e32 v158, 1.0, v159
	v_mul_f32_e32 v159, 0xbfb8aa3b, v32
	v_rcp_f32_e32 v242, v158
	v_add_f32_e32 v158, 1.0, v167
	v_exp_f32_e32 v159, v159
	v_mul_f32_e32 v167, 0xbfb8aa3b, v33
	v_exp_f32_e32 v167, v167
	v_rcp_f32_e32 v243, v158
	v_add_f32_e32 v158, 1.0, v159
	v_rcp_f32_e32 v244, v158
	v_add_f32_e32 v158, 1.0, v167
	v_mul_f32_e32 v167, 0xbfb8aa3b, v34
	v_exp_f32_e32 v167, v167
	v_rcp_f32_e32 v245, v158
	v_rcp_f32_e32 v153, v153
	v_add_f32_e32 v158, 1.0, v167
	v_rcp_f32_e32 v246, v158
	v_add_f32_e32 v158, 1.0, v168
	v_rcp_f32_e32 v247, v158
	v_rcp_f32_e32 v158, v147
	v_max_f32_e32 v147, 0x1e3ce508, v244
	v_rcp_f32_e32 v168, v147
	v_max_f32_e32 v147, 0x1e3ce508, v241
	v_rcp_f32_e32 v159, v147
	v_max_f32_e32 v147, 0x1e3ce508, v245
	v_rcp_f32_e32 v169, v147
	v_max_f32_e32 v147, 0x1e3ce508, v242
	v_rcp_f32_e32 v170, v147
	v_max_f32_e32 v147, 0x1e3ce508, v246
	v_rcp_f32_e32 v172, v147
	v_max_f32_e32 v147, 0x1e3ce508, v243
	v_rcp_f32_e32 v171, v147
	v_max_f32_e32 v147, 0x1e3ce508, v247
	v_rcp_f32_e32 v173, v147
	v_pk_mul_f32 v[154:155], v[154:155], v[158:159]
	v_pk_mul_f32 v[156:157], v[156:157], v[170:171]
	v_pk_mul_f32 v[158:159], v[152:153], v[168:169]
	v_pk_mul_f32 v[160:161], v[160:161], v[172:173]

; __device__ __forceinline__ f32x4 sigm4(f32x4 v) { return (f32x4){sigmoid_f(v[0]), sigmoid_f(v[1]), sigmoid_f(v[2]), sigmoid_f(v[3])}; }
;     __device__ __forceinline__ void operator()(const f32x4 (&acc)[2][2][4][2], const pg8::Unit& u, int wr, int wc, int fr, int fq) const {
;     ...
;                         f32x4 v0 = acc[ai][bj][m][0], v1 = acc[ai][bj][m][1];
;                         if (act == 5) { v0 = sigm4(v0); v1 = sigm4(v1);
;                             if (bj == 0) { const f32x4 b0 = sigm4(acc[ai][1][m][0]), b1 = sigm4(acc[ai][1][m][1]);
; #pragma unroll
;                                 for (int e = 0; e < 4; ++e) { v0[e] *= __builtin_amdgcn_rcpf(fmaxf(b0[e], 1e-20f)); v1[e] *= __builtin_amdgcn_rcpf(fmaxf(b1[e], 1e-20f)); } } }
.LBB0_366:
	s_andn2_b64 vcc, exec, s[16:17]
	s_cbranch_vccnz .LBB0_368
	v_mul_f32_e32 v147, 0xbfb8aa3b, v20
	v_exp_f32_e32 v147, v147
	v_mul_f32_e32 v152, 0xbfb8aa3b, v21
	v_exp_f32_e32 v152, v152
	v_mul_f32_e32 v154, 0xbfb8aa3b, v23
	v_add_f32_e32 v147, 1.0, v147
	v_exp_f32_e32 v154, v154
	v_add_f32_e32 v153, 1.0, v152
	v_rcp_f32_e32 v152, v147
	v_mul_f32_e32 v147, 0xbfb8aa3b, v22
	v_exp_f32_e32 v147, v147
	v_mul_f32_e32 v155, 0xbfb8aa3b, v29
	v_exp_f32_e32 v155, v155
	v_mul_f32_e32 v167, 0xbfb8aa3b, v27
	v_add_f32_e32 v147, 1.0, v147
	v_rcp_f32_e32 v160, v147
	v_add_f32_e32 v147, 1.0, v154
	v_mul_f32_e32 v154, 0xbfb8aa3b, v28
	v_exp_f32_e32 v154, v154
	v_rcp_f32_e32 v161, v147
	v_exp_f32_e32 v167, v167
	v_mul_f32_e32 v168, 0xbfb8aa3b, v19
	v_add_f32_e32 v147, 1.0, v154
	v_rcp_f32_e32 v154, v147
	v_add_f32_e32 v147, 1.0, v155
	v_mul_f32_e32 v155, 0xbfb8aa3b, v30
	v_exp_f32_e32 v156, v155
	v_mul_f32_e32 v155, 0xbfb8aa3b, v31
	v_exp_f32_e32 v157, v155
	v_rcp_f32_e32 v155, v147
	v_add_f32_e32 v147, 1.0, v156
	v_rcp_f32_e32 v156, v147
	v_add_f32_e32 v147, 1.0, v157
	v_mul_f32_e32 v157, 0xbfb8aa3b, v24
	v_exp_f32_e32 v158, v157
	v_mul_f32_e32 v157, 0xbfb8aa3b, v25
	v_exp_f32_e32 v159, v157
	v_rcp_f32_e32 v157, v147
	v_add_f32_e32 v147, 1.0, v158
	v_rcp_f32_e32 v240, v147
	v_add_f32_e32 v158, 1.0, v159
	v_mul_f32_e32 v159, 0xbfb8aa3b, v26
	v_exp_f32_e32 v159, v159
	v_rcp_f32_e32 v241, v158
	v_exp_f32_e32 v168, v168
	v_max_f32_e32 v147, 0x1e3ce508, v240
	v_add_f32_e32 v158, 1.0, v159
	v_mul_f32_e32 v159, 0xbfb8aa3b, v16
	v_rcp_f32_e32 v242, v158
	v_add_f32_e32 v158, 1.0, v167
	v_exp_f32_e32 v159, v159
	v_mul_f32_e32 v167, 0xbfb8aa3b, v17
	v_exp_f32_e32 v167, v167
	v_rcp_f32_e32 v243, v158
	v_add_f32_e32 v158, 1.0, v159
	v_rcp_f32_e32 v244, v158
	v_add_f32_e32 v158, 1.0, v167
	v_mul_f32_e32 v167, 0xbfb8aa3b, v18
	v_exp_f32_e32 v167, v167
	v_rcp_f32_e32 v245, v158
	v_rcp_f32_e32 v153, v153
	v_add_f32_e32 v158, 1.0, v167
	v_rcp_f32_e32 v246, v158
	v_add_f32_e32 v158, 1.0, v168
	v_rcp_f32_e32 v247, v158
	v_rcp_f32_e32 v158, v147
	v_max_f32_e32 v147, 0x1e3ce508, v244
	v_rcp_f32_e32 v168, v147
	v_max_f32_e32 v147, 0x1e3ce508, v241
	v_rcp_f32_e32 v159, v147
	v_max_f32_e32 v147, 0x1e3ce508, v245
	v_rcp_f32_e32 v169, v147
	v_max_f32_e32 v147, 0x1e3ce508, v242
	v_rcp_f32_e32 v170, v147
	v_max_f32_e32 v147, 0x1e3ce508, v246
	v_rcp_f32_e32 v172, v147
	v_max_f32_e32 v147, 0x1e3ce508, v243
	v_rcp_f32_e32 v171, v147
	v_max_f32_e32 v147, 0x1e3ce508, v247
	v_rcp_f32_e32 v173, v147
	v_pk_mul_f32 v[154:155], v[154:155], v[158:159]
	v_pk_mul_f32 v[156:157], v[156:157], v[170:171]
	v_pk_mul_f32 v[158:159], v[152:153], v[168:169]
	v_pk_mul_f32 v[160:161], v[160:161], v[172:173]

; __device__ __forceinline__ f32x4 sigm4(f32x4 v) { return (f32x4){sigmoid_f(v[0]), sigmoid_f(v[1]), sigmoid_f(v[2]), sigmoid_f(v[3])}; }
;     __device__ __forceinline__ void operator()(const f32x4 (&acc)[2][2][4][2], const pg8::Unit& u, int wr, int wc, int fr, int fq) const {
;     ...
;                         f32x4 v0 = acc[ai][bj][m][0], v1 = acc[ai][bj][m][1];
;                         if (act == 5) { v0 = sigm4(v0); v1 = sigm4(v1);
;                             if (bj == 0) { const f32x4 b0 = sigm4(acc[ai][1][m][0]), b1 = sigm4(acc[ai][1][m][1]);
; #pragma unroll
;                                 for (int e = 0; e < 4; ++e) { v0[e] *= __builtin_amdgcn_rcpf(fmaxf(b0[e], 1e-20f)); v1[e] *= __builtin_amdgcn_rcpf(fmaxf(b1[e], 1e-20f)); } } }
.LBB0_394:
	s_andn2_b64 vcc, exec, s[16:17]
	s_cbranch_vccnz .LBB0_396
	v_mul_f32_e32 v147, 0xbfb8aa3b, v4
	v_exp_f32_e32 v147, v147
	v_mul_f32_e32 v152, 0xbfb8aa3b, v5
	v_exp_f32_e32 v152, v152
	v_mul_f32_e32 v153, 0xbfb8aa3b, v7
	v_add_f32_e32 v147, 1.0, v147
	v_rcp_f32_e32 v156, v147
	v_mul_f32_e32 v147, 0xbfb8aa3b, v6
	v_exp_f32_e32 v147, v147
	v_exp_f32_e32 v153, v153
	v_add_f32_e32 v152, 1.0, v152
	v_rcp_f32_e32 v157, v152
	v_add_f32_e32 v147, 1.0, v147
	v_mul_f32_e32 v152, 0xbfb8aa3b, v12
	v_rcp_f32_e32 v158, v147
	v_add_f32_e32 v147, 1.0, v153
	v_exp_f32_e32 v152, v152
	v_mul_f32_e32 v153, 0xbfb8aa3b, v13
	v_exp_f32_e32 v153, v153
	v_rcp_f32_e32 v159, v147
	v_add_f32_e32 v147, 1.0, v152
	v_rcp_f32_e32 v152, v147
	v_add_f32_e32 v147, 1.0, v153
	v_mul_f32_e32 v153, 0xbfb8aa3b, v14
	v_exp_f32_e32 v154, v153
	v_mul_f32_e32 v153, 0xbfb8aa3b, v15
	v_exp_f32_e32 v155, v153
	v_rcp_f32_e32 v153, v147
	v_add_f32_e32 v147, 1.0, v154
	v_rcp_f32_e32 v154, v147
	v_add_f32_e32 v147, 1.0, v155
	v_mul_f32_e32 v155, 0xbfb8aa3b, v8
	v_exp_f32_e32 v160, v155
	v_mul_f32_e32 v155, 0xbfb8aa3b, v9
	v_exp_f32_e32 v161, v155
	v_rcp_f32_e32 v155, v147
	v_add_f32_e32 v147, 1.0, v160
	v_mul_f32_e32 v167, 0xbfb8aa3b, v11
	v_add_f32_e32 v160, 1.0, v161
	v_mul_f32_e32 v161, 0xbfb8aa3b, v10
	v_exp_f32_e32 v161, v161
	v_exp_f32_e32 v167, v167
	v_rcp_f32_e32 v241, v160
	v_mul_f32_e32 v168, 0xbfb8aa3b, v3
	v_add_f32_e32 v160, 1.0, v161
	v_mul_f32_e32 v161, 0xbfb8aa3b, v0
	v_rcp_f32_e32 v242, v160
	v_add_f32_e32 v160, 1.0, v167
	v_exp_f32_e32 v161, v161
	v_mul_f32_e32 v167, 0xbfb8aa3b, v1
	v_exp_f32_e32 v167, v167
	v_rcp_f32_e32 v243, v160
	v_add_f32_e32 v160, 1.0, v161
	v_rcp_f32_e32 v244, v160
	v_add_f32_e32 v160, 1.0, v167
	v_mul_f32_e32 v167, 0xbfb8aa3b, v2
	v_exp_f32_e32 v167, v167
	v_rcp_f32_e32 v240, v147
	v_exp_f32_e32 v168, v168
	v_rcp_f32_e32 v245, v160
	v_add_f32_e32 v160, 1.0, v167
	v_rcp_f32_e32 v246, v160
	v_add_f32_e32 v160, 1.0, v168
	v_max_f32_e32 v147, 0x1e3ce508, v240
	v_rcp_f32_e32 v247, v160
	v_rcp_f32_e32 v160, v147
	v_max_f32_e32 v147, 0x1e3ce508, v244
	v_rcp_f32_e32 v168, v147
	v_max_f32_e32 v147, 0x1e3ce508, v241
	v_rcp_f32_e32 v161, v147
	v_max_f32_e32 v147, 0x1e3ce508, v245
	v_rcp_f32_e32 v169, v147
	v_max_f32_e32 v147, 0x1e3ce508, v242
	v_rcp_f32_e32 v170, v147
	v_max_f32_e32 v147, 0x1e3ce508, v246
	v_rcp_f32_e32 v172, v147
	v_max_f32_e32 v147, 0x1e3ce508, v243
	v_rcp_f32_e32 v171, v147
	v_max_f32_e32 v147, 0x1e3ce508, v247
	v_rcp_f32_e32 v173, v147
	v_pk_mul_f32 v[152:153], v[152:153], v[160:161]
	v_pk_mul_f32 v[154:155], v[154:155], v[170:171]
	v_pk_mul_f32 v[156:157], v[156:157], v[168:169]
	v_pk_mul_f32 v[158:159], v[158:159], v[172:173]

; __device__ __forceinline__ f32x4 sigm4(f32x4 v) { return (f32x4){sigmoid_f(v[0]), sigmoid_f(v[1]), sigmoid_f(v[2]), sigmoid_f(v[3])}; }
;     __device__ __forceinline__ void operator()(const f32x4 (&acc)[2][2][4][2], const pg8::Unit& u, int wr, int wc, int fr, int fq) const {
;     ...
;                     for (int bj = 0; bj < 2; ++bj) {
;                         f32x4 v0 = acc[ai][bj][m][0], v1 = acc[ai][bj][m][1];
;                         if (act == 5) { v0 = sigm4(v0); v1 = sigm4(v1);
.LBB0_408:
	s_andn2_b64 vcc, exec, s[8:9]
	s_cbranch_vccnz .LBB0_410
	v_mov_b64_e32 v[150:151], v[240:241]
	v_mov_b64_e32 v[152:153], v[242:243]
	v_mov_b64_e32 v[154:155], v[244:245]
	v_mov_b64_e32 v[156:157], v[246:247]
